# the four shifted-V loads of a (token tile, head) block issued together with one wait, not four drains
# speedup vs baseline: 1.0092x; 1.0052x over previous
; #define LAS __attribute__((address_space(3)))
; __device__ void phase_rwkv_post(const Params& p, bf16_t* ymix, LAS unsigned char* lds, int wg, int nwg) {
;     ...
;             for (int hh = 0; hh < 4; ++hh) {
;                 const int h = hg * 4 + hh;
;                 f32x4 y[4], vc[4], vp[4];
; #pragma unroll
;                 for (int nt = 0; nt < 4; ++nt) { const size_t e = ((size_t)((int)(m / SEQ) * 32 + h) * SEQ + (m % SEQ)) * 64 + 16 * nt + 4 * fq;
;                     y[nt] = ld4bf(YRAW + e); vc[nt] = ld4bf(V + e); vp[nt] = (f32x4){0.f, 0.f, 0.f, 0.f}; if (hp) vp[nt] = ld4bf(V + e - 64); }
;                 const float bon = BON[(m * 32 + h) * 2] + BON[(m * 32 + h) * 2 + 1];
;                 f32x4 muv4[4], gw4[4], gb4[4];
; #pragma unroll
;                 for (int nt = 0; nt < 4; ++nt) { const int c = h * 64 + 16 * nt + 4 * fq; muv4[nt] = *(const f32x4*)(mu + MU_V + c); gw4[nt] = *(const f32x4*)(p.in[I_GNW] + c); gb4[nt] = *(const f32x4*)(p.in[I_GNB] + c); }
;                 f32x4 acc[4];
; #pragma unroll
;                 for (int nt = 0; nt < 4; ++nt) acc[nt] = (f32x4){0.f, 0.f, 0.f, 0.f};
; #pragma unroll
;                 for (int ks = 0; ks < 8; ++ks)
; #pragma unroll
;                     for (int nt = 0; nt < 4; ++nt) acc[nt] = __builtin_amdgcn_mfma_f32_16x16x32_bf16(*(LAS const bf16x8*)(lds + ((64 * hh + 16 * nt + fr) * 264 + 32 * ks + 8 * fq) * 2), af[ks], acc[nt], 0, 0, 0);
.LBB0_893:
	s_or_b64 exec, exec, s[28:29]
	s_waitcnt vmcnt(0)
	s_and_saveexec_b64 s[98:99], s[2:3]
	v_lshlrev_b32_e32 v98, 16, v240
	v_and_b32_e32 v99, 0xffff0000, v240
	v_lshlrev_b32_e32 v100, 16, v241
	v_and_b32_e32 v102, 0xffff0000, v241
	v_lshlrev_b32_e32 v96, 16, v242
	v_and_b32_e32 v101, 0xffff0000, v242
	v_lshlrev_b32_e32 v103, 16, v243
	v_and_b32_e32 v104, 0xffff0000, v243
	v_lshlrev_b32_e32 v105, 16, v244
	v_and_b32_e32 v106, 0xffff0000, v244
	v_lshlrev_b32_e32 v107, 16, v245
	v_and_b32_e32 v108, 0xffff0000, v245
	v_lshlrev_b32_e32 v97, 16, v246
	v_and_b32_e32 v109, 0xffff0000, v246
	v_lshlrev_b32_e32 v110, 16, v247
	v_and_b32_e32 v111, 0xffff0000, v247
	s_or_b64 exec, exec, s[98:99]
	ds_read_b128 v[60:63], v34
	ds_read_b128 v[70:73], v34 offset:8448
	ds_read_b128 v[112:115], v34 offset:64
	s_waitcnt vmcnt(7)
	v_lshlrev_b32_e32 v191, 16, v79
	v_lshlrev_b32_e32 v190, 16, v78
	s_waitcnt lgkmcnt(2)
	v_mfma_f32_16x16x32_bf16 v[116:119], v[60:63], v[0:3], 0
	ds_read_b128 v[60:63], v34 offset:16896
	ds_read_b128 v[120:123], v34 offset:8512
	v_and_b32_e32 v193, 0xffff0000, v79
	v_and_b32_e32 v192, 0xffff0000, v78
	s_waitcnt lgkmcnt(3)
	v_mfma_f32_16x16x32_bf16 v[124:127], v[70:73], v[0:3], 0
	ds_read_b128 v[70:73], v34 offset:25344
	ds_read_b128 v[128:131], v34 offset:16960
	ds_read_b128 v[136:139], v34 offset:25408
	v_lshl_add_u64 v[78:79], s[14:15], 0, v[54:55]
	s_waitcnt lgkmcnt(4)
	v_mfma_f32_16x16x32_bf16 v[132:135], v[60:63], v[0:3], 0
	v_add_u32_e32 v198, s36, v95
	v_ashrrev_i32_e32 v199, 31, v198
	s_waitcnt vmcnt(5)
	v_lshlrev_b32_e32 v83, 16, v85
	v_mfma_f32_16x16x32_bf16 v[112:115], v[112:115], v[4:7], v[116:119]
	v_lshlrev_b32_e32 v82, 16, v84
	v_and_b32_e32 v189, 0xffff0000, v85
	v_and_b32_e32 v188, 0xffff0000, v84
	s_waitcnt lgkmcnt(3)
	v_mfma_f32_16x16x32_bf16 v[116:119], v[120:123], v[4:7], v[124:127]
	ds_read_b128 v[120:123], v34 offset:128
	v_add_u32_e32 v200, 16, v198
	v_ashrrev_i32_e32 v201, 31, v200
	s_waitcnt lgkmcnt(2)
	v_mfma_f32_16x16x32_bf16 v[124:127], v[128:131], v[4:7], v[132:135]
	ds_read_b128 v[128:131], v34 offset:8576
	s_waitcnt vmcnt(4)
	v_lshlrev_b32_e32 v86, 16, v58
	v_and_b32_e32 v87, 0xffff0000, v58
	v_mfma_f32_16x16x32_bf16 v[140:143], v[70:73], v[0:3], 0
	s_waitcnt vmcnt(1)
	v_and_b32_e32 v61, 0xffff0000, v64
	v_lshlrev_b32_e32 v72, 16, v74
	v_and_b32_e32 v73, 0xffff0000, v74
	s_waitcnt lgkmcnt(2)
	v_mfma_f32_16x16x32_bf16 v[132:135], v[136:139], v[4:7], v[140:143]
	ds_read_b128 v[136:139], v34 offset:17024
	s_nop 1
	ds_read_b128 v[140:143], v34 offset:192
	v_lshlrev_b32_e32 v74, 16, v75
	v_and_b32_e32 v75, 0xffff0000, v75
	s_waitcnt lgkmcnt(3)
	v_mfma_f32_16x16x32_bf16 v[112:115], v[120:123], v[8:11], v[112:115]
	ds_read_b128 v[120:123], v34 offset:25472
	ds_read_b128 v[144:147], v34 offset:8640
	global_load_dwordx2 v[196:197], v[78:79], off
	v_lshlrev_b64 v[78:79], 2, v[198:199]
	s_waitcnt lgkmcnt(4)
	v_mfma_f32_16x16x32_bf16 v[116:119], v[128:131], v[8:11], v[116:119]
	ds_read_b128 v[128:131], v34 offset:17088
	v_lshl_add_u64 v[84:85], s[6:7], 0, v[78:79]
	v_lshl_add_u64 v[180:181], s[68:69], 0, v[78:79]
	s_waitcnt lgkmcnt(4)
	v_mfma_f32_16x16x32_bf16 v[124:127], v[136:139], v[8:11], v[124:127]
	ds_read_b128 v[136:139], v34 offset:25536
	v_lshl_add_u64 v[184:185], s[70:71], 0, v[78:79]
	v_lshl_add_u64 v[78:79], v[200:201], 2, s[6:7]
	s_waitcnt lgkmcnt(3)
	v_mfma_f32_16x16x32_bf16 v[120:123], v[120:123], v[8:11], v[132:135]
	v_lshlrev_b32_e32 v63, 16, v64
	v_lshlrev_b32_e32 v67, 16, v65
	v_and_b32_e32 v65, 0xffff0000, v65
	ds_read_b128 v[132:135], v34 offset:256
	s_waitcnt lgkmcnt(2)
	v_mfma_f32_16x16x32_bf16 v[124:127], v[128:131], v[12:15], v[124:127]
	ds_read_b128 v[128:131], v34 offset:8704
	v_add_f32_e32 v66, v72, v73
	v_add_f32_e32 v64, v74, v75
	v_mfma_f32_16x16x32_bf16 v[112:115], v[140:143], v[12:15], v[112:115]
	v_sub_f32_e32 v101, v101, v87
	v_lshlrev_b32_e32 v76, 16, v80
	v_and_b32_e32 v77, 0xffff0000, v80
	v_mfma_f32_16x16x32_bf16 v[116:119], v[144:147], v[12:15], v[116:119]
	v_lshlrev_b32_e32 v80, 16, v81
	v_and_b32_e32 v81, 0xffff0000, v81
	s_waitcnt vmcnt(1)
	v_lshlrev_b32_e32 v70, 16, v68
	s_waitcnt lgkmcnt(2)
	v_mfma_f32_16x16x32_bf16 v[120:123], v[136:139], v[12:15], v[120:123]
	ds_read_b128 v[136:139], v34 offset:17152
	ds_read_b128 v[140:143], v34 offset:320
	v_and_b32_e32 v71, 0xffff0000, v68
	v_lshlrev_b32_e32 v68, 16, v69
	s_waitcnt lgkmcnt(3)
	v_mfma_f32_16x16x32_bf16 v[112:115], v[132:135], v[16:19], v[112:115]
	ds_read_b128 v[132:135], v34 offset:25600
	ds_read_b128 v[144:147], v34 offset:8768
	ds_read_b128 v[148:151], v34 offset:25664
	v_and_b32_e32 v69, 0xffff0000, v69
	s_waitcnt lgkmcnt(5)
	v_mfma_f32_16x16x32_bf16 v[116:119], v[128:131], v[16:19], v[116:119]
	ds_read_b128 v[128:131], v34 offset:17216
	s_add_i32 s36, s36, 64
	v_lshl_add_u64 v[54:55], v[54:55], 0, 8
	s_waitcnt lgkmcnt(5)
	v_mfma_f32_16x16x32_bf16 v[124:127], v[136:139], v[16:19], v[124:127]
	global_load_dwordx4 v[136:139], v[84:85], off
	v_add_u32_e32 v84, 32, v198
	v_ashrrev_i32_e32 v85, 31, v84
	s_waitcnt lgkmcnt(3)
	v_mfma_f32_16x16x32_bf16 v[120:123], v[132:135], v[16:19], v[120:123]
	v_lshl_add_u64 v[164:165], v[84:85], 2, s[6:7]
	v_lshl_add_u64 v[48:49], v[48:49], 0, s[20:21]
	s_cmpk_eq_i32 s36, 0x100
	v_mfma_f32_16x16x32_bf16 v[112:115], v[140:143], v[20:23], v[112:115]
	global_load_dwordx4 v[132:135], v[180:181], off
	global_load_dwordx4 v[140:143], v[180:181], off offset:64
	v_lshl_add_u64 v[50:51], v[50:51], 0, s[20:21]
	s_waitcnt lgkmcnt(2)
	v_mfma_f32_16x16x32_bf16 v[116:119], v[144:147], v[20:23], v[116:119]
	global_load_dwordx4 v[144:147], v[184:185], off
	global_load_dwordx4 v[152:155], v[184:185], off offset:64
	ds_read_b128 v[156:159], v34 offset:384
	s_waitcnt lgkmcnt(1)
; #define LAS __attribute__((address_space(3)))
; __device__ __forceinline__ unsigned cvt_pk_bf16_c(float lo, float hi) { const f32x2_ v = {lo, hi}; return __builtin_bit_cast(unsigned, __builtin_convertvector(v, bf16v2_)); }
; __device__ __forceinline__ float sumsq4(f32x4 h) { return (h.x * h.x + h.y * h.y) + (h.z * h.z + h.w * h.w); }
; __device__ void phase_rwkv_post(const Params& p, bf16_t* ymix, LAS unsigned char* lds, int wg, int nwg) {
;     ...
;                 for (int ks = 0; ks < 8; ++ks)
; #pragma unroll
;                     for (int nt = 0; nt < 4; ++nt) acc[nt] = __builtin_amdgcn_mfma_f32_16x16x32_bf16(*(LAS const bf16x8*)(lds + ((64 * hh + 16 * nt + fr) * 264 + 32 * ks + 8 * fq) * 2), af[ks], acc[nt], 0, 0, 0);
;                 float s1 = 0.f;
; #pragma unroll
;                 for (int nt = 0; nt < 4; ++nt) s1 += (y[nt].x + y[nt].y) + (y[nt].z + y[nt].w);
;                 s1 += __shfl_xor(s1, 16); s1 += __shfl_xor(s1, 32);
;                 const float mean = s1 * (1.f / 64.f); float s2 = 0.f;
; #pragma unroll
;                 for (int nt = 0; nt < 4; ++nt) { y[nt] = y[nt] - mean; s2 += sumsq4(y[nt]); }
;                 s2 += __shfl_xor(s2, 16); s2 += __shfl_xor(s2, 32);
;                 const float rstd = __builtin_amdgcn_rsqf(s2 * (1.f / 64.f) + GN_EPS);
; #pragma unroll
;                 for (int nt = 0; nt < 4; ++nt) {
;                     const int c = h * 64 + 16 * nt + 4 * fq;
;                     const f32x4 muv = muv4[nt], gw = gw4[nt], gb = gb4[nt];
;                     const f32x4 v4 = vc[nt] + (vp[nt] - vc[nt]) * muv;
;                     const f32x4 o = (y[nt] * rstd * gw + gb + v4 * bon) * acc[nt];
;                     u32x2 w; w.x = pg8::cvt_pk_bf16_c(o.x, o.y); w.y = pg8::cvt_pk_bf16_c(o.z, o.w);
;                     *(u32x2*)(ymix + m * D_MIX + 2048 + c) = w;
	v_mfma_f32_16x16x32_bf16 v[124:127], v[128:131], v[20:23], v[124:127]
	ds_read_b128 v[128:131], v34 offset:8832
	v_mfma_f32_16x16x32_bf16 v[120:123], v[148:151], v[20:23], v[120:123]
	ds_read_b128 v[148:151], v34 offset:17280
	ds_read_b128 v[160:163], v34 offset:448
	s_waitcnt lgkmcnt(1)
	v_mfma_f32_16x16x32_bf16 v[124:127], v[148:151], v[24:27], v[124:127]
	v_add_f32_e64 v148, v190, v192
	v_add_f32_e64 v149, v191, v193
	v_pk_add_f32 v[150:151], v[66:67], v[64:65]
	v_add_f32_e32 v58, v148, v149
	v_mfma_f32_16x16x32_bf16 v[112:115], v[156:159], v[24:27], v[112:115]
	global_load_dwordx4 v[156:159], v[78:79], off
	s_nop 0
	global_load_dwordx4 v[164:167], v[164:165], off
	v_pk_add_f32 v[148:149], v[82:83], v[188:189]
	ds_read_b128 v[168:171], v34 offset:25728
	ds_read_b128 v[172:175], v34 offset:8896
	v_pk_add_f32 v[148:149], v[148:149], v[148:149] op_sel:[0,1] op_sel_hi:[1,0]
	v_add_f32_e32 v62, 0, v58
	v_mov_b32_e32 v149, v61
	v_add_u32_e32 v78, 48, v198
	v_pk_add_f32 v[148:149], v[62:63], v[148:149]
	v_ashrrev_i32_e32 v79, 31, v78
	v_pk_add_f32 v[148:149], v[148:149], v[150:151]
	v_mfma_f32_16x16x32_bf16 v[116:119], v[128:131], v[24:27], v[116:119]
	v_add_f32_e32 v58, v148, v149
	v_lshl_add_u64 v[148:149], v[78:79], 2, s[6:7]
	ds_read_b128 v[128:131], v34 offset:17344
	ds_read_b128 v[176:179], v34 offset:25792
	s_waitcnt lgkmcnt(3)
	v_mfma_f32_16x16x32_bf16 v[120:123], v[168:171], v[24:27], v[120:123]
	global_load_dwordx4 v[148:151], v[148:149], off
	ds_bpermute_b32 v60, v41, v58
	s_waitcnt vmcnt(8)
	v_add_f32_e32 v66, v196, v197
	v_mfma_f32_16x16x32_bf16 v[112:115], v[160:163], v[28:31], v[112:115]
	global_load_dwordx4 v[160:163], v[180:181], off offset:128
	global_load_dwordx4 v[168:171], v[180:181], off offset:192
	s_nop 0
	global_load_dwordx4 v[180:183], v[184:185], off offset:128
	s_nop 0
	global_load_dwordx4 v[184:187], v[184:185], off offset:192
	v_add_u32_e32 v34, 0x8400, v34
	s_waitcnt lgkmcnt(0)
	v_add_f32_e32 v58, v58, v60
	ds_bpermute_b32 v60, v88, v58
	v_mfma_f32_16x16x32_bf16 v[116:119], v[172:175], v[28:31], v[116:119]
	s_waitcnt lgkmcnt(0)
	v_add_f32_e32 v60, v58, v60
	v_fmac_f32_e32 v192, 0xbc800000, v60
	v_fmac_f32_e32 v193, 0xbc800000, v60
	v_fmac_f32_e32 v191, 0xbc800000, v60
	v_fmac_f32_e32 v190, 0xbc800000, v60
	v_mov_b32_e32 v172, v191
	v_mov_b32_e32 v173, v193
	v_mov_b32_e32 v191, v192
	v_pk_mul_f32 v[174:175], v[172:173], v[172:173]
	v_pk_mul_f32 v[192:193], v[190:191], v[190:191]
	v_fmac_f32_e32 v188, 0xbc800000, v60
	v_pk_mov_b32 v[202:203], v[192:193], v[174:175] op_sel:[1,0]
	v_mov_b32_e32 v193, v175
	v_fmac_f32_e32 v189, 0xbc800000, v60
	v_fmac_f32_e32 v83, 0xbc800000, v60
	v_pk_add_f32 v[174:175], v[202:203], v[192:193]
	v_fmac_f32_e32 v82, 0xbc800000, v60
	v_mov_b32_e32 v192, v83
	v_mov_b32_e32 v193, v189
	v_mov_b32_e32 v83, v188
	v_pk_mul_f32 v[202:203], v[192:193], v[192:193]
	v_pk_mul_f32 v[188:189], v[82:83], v[82:83]
	v_fmac_f32_e32 v72, 0xbc800000, v60
	v_pk_mov_b32 v[204:205], v[188:189], v[202:203] op_sel:[1,0]
	v_mov_b32_e32 v189, v203
	v_fmac_f32_e32 v73, 0xbc800000, v60
	v_fmac_f32_e32 v74, 0xbc800000, v60
	v_mul_f32_e32 v58, v72, v72
	v_pk_add_f32 v[188:189], v[204:205], v[188:189]
	v_fmac_f32_e32 v75, 0xbc800000, v60
	v_pk_fma_f32 v[202:203], v[72:73], v[72:73], v[58:59] op_sel_hi:[1,1,0]
	v_mul_f32_e32 v58, v74, v74
	v_pk_add_f32 v[174:175], v[174:175], v[174:175] op_sel_hi:[0,1]
	v_pk_add_f32 v[188:189], v[188:189], v[188:189] op_sel_hi:[0,1]
	v_pk_fma_f32 v[204:205], v[74:75], v[74:75], v[58:59] op_sel_hi:[1,1,0]
	v_fmac_f32_e32 v65, 0xbc800000, v60
	v_fmac_f32_e32 v67, 0xbc800000, v60
	v_fmac_f32_e32 v61, 0xbc800000, v60
	v_fmac_f32_e32 v63, 0xbc800000, v60
	v_mul_f32_e32 v202, v63, v63
	v_mul_f32_e32 v204, v61, v61
	v_mul_f32_e32 v174, v67, v67
	v_mul_f32_e32 v188, v65, v65
	v_pk_add_f32 v[202:203], v[202:203], v[204:205]
	v_pk_add_f32 v[174:175], v[174:175], v[188:189]
	v_mfma_f32_16x16x32_bf16 v[124:127], v[128:131], v[28:31], v[124:127]
	v_add_f32_e64 v174, v202, v174
	v_add_f32_e64 v175, v203, v175
	v_lshlrev_b32_e32 v128, 16, v57
	v_add_f32_e32 v58, v174, v175
	ds_bpermute_b32 v60, v41, v58
	v_and_b32_e32 v129, 0xffff0000, v57
	v_lshlrev_b32_e32 v174, 16, v59
	v_and_b32_e32 v175, 0xffff0000, v59
	v_lshlrev_b32_e32 v188, 16, v56
	s_waitcnt lgkmcnt(0)
	v_add_f32_e32 v60, v58, v60
	ds_bpermute_b32 v62, v88, v60
	v_and_b32_e32 v189, 0xffff0000, v56
	v_mfma_f32_16x16x32_bf16 v[56:59], v[176:179], v[28:31], v[120:123]
	v_sub_f32_e32 v99, v99, v189
	v_sub_f32_e32 v98, v98, v188
	s_waitcnt lgkmcnt(0)
	v_add_f32_e32 v60, v60, v62
	v_fmamk_f32 v60, v60, 0x3c800000, v92
	v_rsq_f32_e32 v62, v60
	v_sub_f32_e32 v121, v102, v129
	v_sub_f32_e32 v120, v100, v128
	s_waitcnt vmcnt(11)
	v_pk_fma_f32 v[120:121], v[120:121], v[138:139], v[128:129]
	v_pk_mul_f32 v[122:123], v[190:191], v[62:63] op_sel_hi:[1,0]
	v_pk_mul_f32 v[128:129], v[172:173], v[62:63] op_sel_hi:[1,0]
	v_pk_fma_f32 v[98:99], v[98:99], v[136:137], v[188:189]
	s_waitcnt vmcnt(8)
	v_pk_fma_f32 v[128:129], v[134:135], v[128:129], v[146:147]
	v_pk_fma_f32 v[122:123], v[132:133], v[122:123], v[144:145]
	v_pk_fma_f32 v[120:121], v[66:67], v[120:121], v[128:129] op_sel_hi:[0,1,1]
	v_pk_fma_f32 v[98:99], v[66:67], v[98:99], v[122:123] op_sel_hi:[0,1,1]
	v_pk_mul_f32 v[114:115], v[114:115], v[120:121]
	v_pk_mul_f32 v[98:99], v[112:113], v[98:99]
	v_lshl_add_u64 v[112:113], v[198:199], 1, v[52:53]
	v_cvt_pk_bf16_f32 v98, v98, v99
	v_cvt_pk_bf16_f32 v99, v114, v115
	v_sub_f32_e32 v100, v96, v86
	global_store_dwordx2 v[112:113], v[98:99], off
	v_sub_f32_e32 v99, v104, v175
	v_sub_f32_e32 v98, v103, v174
	s_waitcnt vmcnt(7)
; __device__ __forceinline__ unsigned cvt_pk_bf16_c(float lo, float hi) { const f32x2_ v = {lo, hi}; return __builtin_bit_cast(unsigned, __builtin_convertvector(v, bf16v2_)); }
; __device__ void phase_rwkv_post(const Params& p, bf16_t* ymix, LAS unsigned char* lds, int wg, int nwg) {
;     ...
;                 f32x4 y[4], vc[4], vp[4];
; #pragma unroll
;                 for (int nt = 0; nt < 4; ++nt) { const size_t e = ((size_t)((int)(m / SEQ) * 32 + h) * SEQ + (m % SEQ)) * 64 + 16 * nt + 4 * fq;
;                     y[nt] = ld4bf(YRAW + e); vc[nt] = ld4bf(V + e); vp[nt] = (f32x4){0.f, 0.f, 0.f, 0.f}; if (hp) vp[nt] = ld4bf(V + e - 64); }
;     ...
;                 for (int nt = 0; nt < 4; ++nt) {
;                     const int c = h * 64 + 16 * nt + 4 * fq;
;                     const f32x4 muv = muv4[nt], gw = gw4[nt], gb = gb4[nt];
;                     const f32x4 v4 = vc[nt] + (vp[nt] - vc[nt]) * muv;
;                     const f32x4 o = (y[nt] * rstd * gw + gb + v4 * bon) * acc[nt];
;                     u32x2 w; w.x = pg8::cvt_pk_bf16_c(o.x, o.y); w.y = pg8::cvt_pk_bf16_c(o.z, o.w);
;                     *(u32x2*)(ymix + m * D_MIX + 2048 + c) = w;
;                 }
	v_pk_fma_f32 v[86:87], v[100:101], v[156:157], v[86:87]
	v_pk_mul_f32 v[82:83], v[82:83], v[62:63] op_sel_hi:[1,0]
	v_pk_mul_f32 v[100:101], v[192:193], v[62:63] op_sel_hi:[1,0]
	v_pk_fma_f32 v[98:99], v[98:99], v[158:159], v[174:175]
	v_pk_fma_f32 v[100:101], v[142:143], v[100:101], v[154:155]
	v_pk_fma_f32 v[82:83], v[140:141], v[82:83], v[152:153]
	v_pk_mul_f32 v[72:73], v[72:73], v[62:63] op_sel_hi:[1,0]
	v_pk_fma_f32 v[82:83], v[66:67], v[86:87], v[82:83] op_sel_hi:[0,1,1]
	v_pk_fma_f32 v[86:87], v[66:67], v[98:99], v[100:101] op_sel_hi:[0,1,1]
	v_pk_mul_f32 v[86:87], v[118:119], v[86:87]
	v_pk_mul_f32 v[82:83], v[116:117], v[82:83]
	v_pk_mul_f32 v[74:75], v[74:75], v[62:63] op_sel_hi:[1,0]
	v_cvt_pk_bf16_f32 v82, v82, v83
	v_cvt_pk_bf16_f32 v83, v86, v87
	v_lshl_add_u64 v[86:87], v[200:201], 1, v[52:53]
	global_store_dwordx2 v[86:87], v[82:83], off
	v_sub_f32_e32 v83, v108, v81
	v_sub_f32_e32 v82, v107, v80
	v_sub_f32_e32 v87, v106, v77
	v_sub_f32_e32 v86, v105, v76
	s_waitcnt vmcnt(7)
	v_pk_fma_f32 v[76:77], v[86:87], v[164:165], v[76:77]
	v_pk_fma_f32 v[80:81], v[82:83], v[166:167], v[80:81]
	s_waitcnt vmcnt(3)
	v_pk_fma_f32 v[74:75], v[162:163], v[74:75], v[182:183]
	v_pk_fma_f32 v[72:73], v[160:161], v[72:73], v[180:181]
	v_pk_fma_f32 v[74:75], v[66:67], v[80:81], v[74:75] op_sel_hi:[0,1,1]
	v_pk_fma_f32 v[72:73], v[66:67], v[76:77], v[72:73] op_sel_hi:[0,1,1]
	v_pk_mul_f32 v[74:75], v[126:127], v[74:75]
	v_pk_mul_f32 v[72:73], v[124:125], v[72:73]
	v_mov_b32_e32 v60, v63
	v_cvt_pk_bf16_f32 v72, v72, v73
	v_cvt_pk_bf16_f32 v73, v74, v75
	v_lshl_add_u64 v[74:75], v[84:85], 1, v[52:53]
	v_mov_b32_e32 v64, v67
	global_store_dwordx2 v[74:75], v[72:73], off
	v_sub_f32_e32 v73, v111, v69
	v_sub_f32_e32 v72, v110, v68
	v_sub_f32_e32 v75, v109, v71
	v_sub_f32_e32 v74, v97, v70
	v_pk_mul_f32 v[60:61], v[60:61], v[62:63] op_sel_hi:[1,0]
	v_pk_mul_f32 v[62:63], v[64:65], v[62:63] op_sel_hi:[1,0]
	v_pk_fma_f32 v[70:71], v[74:75], v[148:149], v[70:71]
	v_pk_fma_f32 v[68:69], v[72:73], v[150:151], v[68:69]
	s_waitcnt vmcnt(3)
	v_pk_fma_f32 v[62:63], v[170:171], v[62:63], v[186:187]
	v_pk_fma_f32 v[60:61], v[168:169], v[60:61], v[184:185]
	v_pk_fma_f32 v[62:63], v[66:67], v[68:69], v[62:63] op_sel_hi:[0,1,1]
	v_pk_fma_f32 v[60:61], v[66:67], v[70:71], v[60:61] op_sel_hi:[0,1,1]
	v_pk_mul_f32 v[58:59], v[58:59], v[62:63]
	v_pk_mul_f32 v[56:57], v[56:57], v[60:61]
	s_nop 0
	v_cvt_pk_bf16_f32 v56, v56, v57
	v_cvt_pk_bf16_f32 v57, v58, v59
	v_lshl_add_u64 v[58:59], v[78:79], 1, v[52:53]
	global_store_dwordx2 v[58:59], v[56:57], off
	s_cbranch_scc1 .LBB0_891
.LBB0_894:
	v_lshl_add_u64 v[58:59], s[14:15], 0, v[48:49]
	v_add_co_u32_e32 v56, vcc, 0x1b800000, v58
	v_mov_b32_e32 v96, 0
	s_nop 0
	v_addc_co_u32_e32 v57, vcc, 0, v59, vcc
	v_add_co_u32_e32 v60, vcc, 0xe000000, v58
	v_mov_b32_e32 v98, 0
	s_nop 0
	v_addc_co_u32_e32 v61, vcc, 0, v59, vcc
	global_load_dwordx2 v[78:79], v[56:57], off
	s_nop 0
	global_load_dwordx2 v[56:57], v[60:61], off
	v_mov_b32_e32 v99, 0
	v_mov_b32_e32 v100, 0
	v_mov_b32_e32 v102, 0
	s_and_saveexec_b64 s[28:29], s[2:3]
	s_cbranch_execz .LBB0_896
	v_add_co_u32_e32 v58, vcc, 0xdfff000, v58
	s_nop 1
	v_addc_co_u32_e32 v59, vcc, 0, v59, vcc
	global_load_dwordx2 v[240:241], v[58:59], off offset:3968
.LBB0_896:
	s_or_b64 exec, exec, s[28:29]
	v_lshl_add_u64 v[60:61], s[14:15], 0, v[50:51]
	v_add_co_u32_e32 v58, vcc, 0x1b800000, v60
	v_mov_b32_e32 v101, 0
	s_nop 0
	v_addc_co_u32_e32 v59, vcc, 0, v61, vcc
	v_add_co_u32_e32 v62, vcc, 0xe000000, v60
	v_mov_b32_e32 v103, 0
	s_nop 0
	v_addc_co_u32_e32 v63, vcc, 0, v61, vcc
	global_load_dwordx2 v[84:85], v[58:59], off offset:32
	s_nop 0
	global_load_dwordx2 v[58:59], v[62:63], off offset:32
	v_mov_b32_e32 v104, 0
	s_and_saveexec_b64 s[28:29], s[2:3]
	s_cbranch_execz .LBB0_898
	v_add_co_u32_e32 v62, vcc, 0xdfff000, v60
	s_nop 1
	v_addc_co_u32_e32 v63, vcc, 0, v61, vcc
	global_load_dwordx2 v[242:243], v[62:63], off offset:4000
.LBB0_898:
	s_or_b64 exec, exec, s[28:29]
	v_add_co_u32_e32 v62, vcc, 0x1b800000, v60
	v_mov_b32_e32 v97, 0
	s_nop 0
	v_addc_co_u32_e32 v63, vcc, 0, v61, vcc
	v_add_co_u32_e32 v64, vcc, 0xe000000, v60
	v_mov_b32_e32 v105, 0
	s_nop 0
	v_addc_co_u32_e32 v65, vcc, 0, v61, vcc
	global_load_dwordx2 v[74:75], v[62:63], off offset:64
	global_load_dwordx2 v[80:81], v[64:65], off offset:64
	v_mov_b32_e32 v106, 0
	v_mov_b32_e32 v107, 0
	v_mov_b32_e32 v108, 0
	s_and_saveexec_b64 s[28:29], s[2:3]
	s_cbranch_execz .LBB0_900
	v_add_co_u32_e32 v62, vcc, 0xdfff000, v60
	s_nop 1
	v_addc_co_u32_e32 v63, vcc, 0, v61, vcc
	global_load_dwordx2 v[244:245], v[62:63], off offset:4032
.LBB0_900:
	s_or_b64 exec, exec, s[28:29]
	v_add_co_u32_e32 v62, vcc, 0x1b800000, v60
	v_mov_b32_e32 v109, 0
	s_nop 0
	v_addc_co_u32_e32 v63, vcc, 0, v61, vcc
	v_add_co_u32_e32 v66, vcc, 0xe000000, v60
	v_mov_b32_e32 v110, 0
	s_nop 0
	v_addc_co_u32_e32 v67, vcc, 0, v61, vcc
	global_load_dwordx2 v[64:65], v[62:63], off offset:96
	global_load_dwordx2 v[68:69], v[66:67], off offset:96
	v_mov_b32_e32 v111, 0
	s_and_saveexec_b64 s[28:29], s[2:3]
	s_cbranch_execz .LBB0_893
	v_add_co_u32_e32 v60, vcc, 0xdfff000, v60
	s_nop 1
	v_addc_co_u32_e32 v61, vcc, 0, v61, vcc
	global_load_dwordx2 v[246:247], v[60:61], off offset:4064
	s_branch .LBB0_893
